# speedup vs baseline: 1.0278x; 1.0081x over previous
; __device__ __forceinline__ void partialSM(f32x16& p0, f32x16& p1, float& m_reg, float& mn, float& alpha) {
;   constexpr float C = SCALE * 1.4426950408889634f;
;   float pmax = p0[0]; for (int r = 1; r < 16; ++r) pmax = fmaxf(pmax, p0[r]); for (int r = 0; r < 16; ++r) pmax = fmaxf(pmax, p1[r]);
;   { auto rr = __builtin_amdgcn_permlane32_swap(__float_as_uint(pmax), __float_as_uint(pmax), false, false);
;     pmax = fmaxf(__uint_as_float(rr[0]), __uint_as_float(rr[1])); }
;   if (__builtin_expect(__all(pmax - m_reg <= THR / SCALE), 1)) { mn = m_reg; alpha = 1.f; }
;   else { mn = fmaxf(m_reg, pmax); alpha = __builtin_amdgcn_exp2f((m_reg - mn) * C); m_reg = mn; }
;   float mnC = -mn * C;
;   for (int r = 0; r < 16; ++r) p0[r] = fmaf(p0[r], C, mnC); for (int r = 0; r < 16; ++r) p1[r] = fmaf(p1[r], C, mnC);
;   for (int r = 0; r < 16; ++r) p0[r] = __builtin_amdgcn_exp2f(p0[r]);
; }
; __device__ __forceinline__ void finishSM(f32x16& p0, f32x16& p1, float alpha, float& l_reg, bf16x8& pa0, bf16x8& pa1, bf16x8& pa2, bf16x8& pa3) {
;   for (int r = 0; r < 16; ++r) p1[r] = __builtin_amdgcn_exp2f(p1[r]);
;   float ps = 0; for (int r = 0; r < 16; ++r) ps += p0[r]; for (int r = 0; r < 16; ++r) ps += p1[r];
;   { auto rr = __builtin_amdgcn_permlane32_swap(__float_as_uint(ps), __float_as_uint(ps), false, false);
;     ps = __uint_as_float(rr[0]) + __uint_as_float(rr[1]); }
;   l_reg = l_reg * alpha + ps;
;     ...
;   PK4(p0, 0, pa0); PK4(p0, 8, pa1); PK4(p1, 0, pa2); PK4(p1, 8, pa3);
;     ...
; }
; __device__ __forceinline__ void qkt(f32x16& p0, f32x16& p1, const bf16_t* Ks, const bf16x8* qr, int r32, int hi) {
;   p0 = f32x16{}; p1 = f32x16{};
;   for (int d0 = 0; d0 < 8; ++d0) { int cb = (d0 * 16 + hi * 8) * 2;
;     bf16x8 b0 = *reinterpret_cast<const bf16x8*>((const char*)Ks + KSWZ(r32, cb));
;     bf16x8 b1 = *reinterpret_cast<const bf16x8*>((const char*)Ks + KSWZ(32 + r32, cb));
;     p0 = __builtin_amdgcn_mfma_f32_32x32x16_bf16(b0, qr[d0], p0, 0, 0, 0);
;     p1 = __builtin_amdgcn_mfma_f32_32x32x16_bf16(b1, qr[d0], p1, 0, 0, 0); }
; }
.Lat_x_top:
	s_add_i32 s8, s13, -2
	s_and_b32 s25, s8, 1
	s_lshl_b32 s24, s25, 14
	s_setprio 1
	s_waitcnt lgkmcnt(5)
	v_mfma_f32_16x16x32_bf16 v[130:133], v[194:197], v[162:165], v[236:239]
	v_mfma_f32_16x16x32_bf16 v[134:137], v[194:197], v[178:181], v[240:243]
	ds_read_b128 v[194:197], v247 offset:8192
	s_waitcnt lgkmcnt(5)
	v_mfma_f32_16x16x32_bf16 v[138:141], v[198:201], v[162:165], v[236:239]
	v_mfma_f32_16x16x32_bf16 v[142:145], v[198:201], v[178:181], v[240:243]
	ds_read_b128 v[198:201], v247 offset:12288
	s_waitcnt lgkmcnt(5)
	v_mfma_f32_16x16x32_bf16 v[146:149], v[202:205], v[162:165], v[236:239]
	v_mfma_f32_16x16x32_bf16 v[150:153], v[202:205], v[178:181], v[240:243]
	ds_read_b128 v[202:205], v228
	s_waitcnt lgkmcnt(5)
	v_mfma_f32_16x16x32_bf16 v[154:157], v[206:209], v[162:165], v[236:239]
	v_mfma_f32_16x16x32_bf16 v[158:161], v[206:209], v[178:181], v[240:243]
	ds_read_b128 v[206:209], v228 offset:4096
	s_waitcnt lgkmcnt(5)
	v_mfma_f32_16x16x32_bf16 v[130:133], v[210:213], v[166:169], v[130:133]
	v_mfma_f32_16x16x32_bf16 v[134:137], v[210:213], v[182:185], v[134:137]
	ds_read_b128 v[210:213], v228 offset:8192
	s_waitcnt lgkmcnt(5)
	v_mfma_f32_16x16x32_bf16 v[138:141], v[214:217], v[166:169], v[138:141]
	v_mfma_f32_16x16x32_bf16 v[142:145], v[214:217], v[182:185], v[142:145]
	ds_read_b128 v[214:217], v228 offset:12288
	s_waitcnt lgkmcnt(5)
	v_mfma_f32_16x16x32_bf16 v[146:149], v[194:197], v[166:169], v[146:149]
	v_mfma_f32_16x16x32_bf16 v[150:153], v[194:197], v[182:185], v[150:153]
	ds_read_b128 v[194:197], v245
	s_waitcnt lgkmcnt(5)
	v_mfma_f32_16x16x32_bf16 v[154:157], v[198:201], v[166:169], v[154:157]
	v_mfma_f32_16x16x32_bf16 v[158:161], v[198:201], v[182:185], v[158:161]
	ds_read_b128 v[198:201], v245 offset:4096
	s_waitcnt lgkmcnt(5)
	v_mfma_f32_16x16x32_bf16 v[130:133], v[202:205], v[170:173], v[130:133]
	v_mfma_f32_16x16x32_bf16 v[134:137], v[202:205], v[186:189], v[134:137]
	ds_read_b128 v[202:205], v245 offset:8192
	s_waitcnt lgkmcnt(5)
	v_mfma_f32_16x16x32_bf16 v[138:141], v[206:209], v[170:173], v[138:141]
	v_mfma_f32_16x16x32_bf16 v[142:145], v[206:209], v[186:189], v[142:145]
	ds_read_b128 v[206:209], v245 offset:12288
	s_waitcnt lgkmcnt(5)
	v_mfma_f32_16x16x32_bf16 v[146:149], v[210:213], v[170:173], v[146:149]
	v_mfma_f32_16x16x32_bf16 v[150:153], v[210:213], v[186:189], v[150:153]
	s_waitcnt lgkmcnt(4)
	v_mfma_f32_16x16x32_bf16 v[154:157], v[214:217], v[170:173], v[154:157]
	v_mfma_f32_16x16x32_bf16 v[158:161], v[214:217], v[186:189], v[158:161]
	s_waitcnt lgkmcnt(3)
	v_mfma_f32_16x16x32_bf16 v[130:133], v[194:197], v[174:177], v[130:133]
	v_mfma_f32_16x16x32_bf16 v[134:137], v[194:197], v[190:193], v[134:137]
	s_waitcnt lgkmcnt(2)
	v_mfma_f32_16x16x32_bf16 v[138:141], v[198:201], v[174:177], v[138:141]
	v_mfma_f32_16x16x32_bf16 v[142:145], v[198:201], v[190:193], v[142:145]
	s_waitcnt lgkmcnt(1)
	v_mfma_f32_16x16x32_bf16 v[146:149], v[202:205], v[174:177], v[146:149]
	v_mfma_f32_16x16x32_bf16 v[150:153], v[202:205], v[190:193], v[150:153]
	s_waitcnt lgkmcnt(0)
	v_mfma_f32_16x16x32_bf16 v[154:157], v[206:209], v[174:177], v[154:157]
	v_mfma_f32_16x16x32_bf16 v[158:161], v[206:209], v[190:193], v[158:161]
	s_setprio 0
	s_nop 6
	v_max3_f32 v194, v130, v131, v132
	v_max3_f32 v194, v194, v133, v138
	v_max3_f32 v194, v194, v139, v140
	v_max3_f32 v194, v194, v141, v146
	v_max3_f32 v194, v194, v147, v148
	v_max3_f32 v194, v194, v149, v154
	v_max3_f32 v194, v194, v155, v156
	v_max_f32_e32 v194, v194, v157
	v_max3_f32 v195, v134, v135, v136
	v_max3_f32 v195, v195, v137, v142
	v_max3_f32 v195, v195, v143, v144
	v_max3_f32 v195, v195, v145, v150
	v_max3_f32 v195, v195, v151, v152
	v_max3_f32 v195, v195, v153, v158
	v_max3_f32 v195, v195, v159, v160
	v_max_f32_e32 v195, v195, v161
	v_max_f32_e32 v196, v194, v195
	v_cmp_nge_f32_e32 vcc, 0x4138aa3b, v196
	s_cbranch_vccnz .Lat_x_rare
	s_cmp_lg_u32 s13, 2
	s_cbranch_scc1 .Lat_x_noresc
; __device__ __forceinline__ int crow(int r, int hi) { return (r & 3) + 8 * (r >> 2) + 4 * hi; }
; __device__ __forceinline__ int crow(int r, int hi) { return (r & 3) + 8 * (r >> 2) + 4 * hi; }
; __device__ __forceinline__ void partialSM(f32x16& p0, f32x16& p1, float& m_reg, float& mn, float& alpha) {
;     ...
;   { auto rr = __builtin_amdgcn_permlane32_swap(__float_as_uint(pmax), __float_as_uint(pmax), false, false);
;     pmax = fmaxf(__uint_as_float(rr[0]), __uint_as_float(rr[1])); }
;   if (__builtin_expect(__all(pmax - m_reg <= THR / SCALE), 1)) { mn = m_reg; alpha = 1.f; }
;   else { mn = fmaxf(m_reg, pmax); alpha = __builtin_amdgcn_exp2f((m_reg - mn) * C); m_reg = mn; }
;   float mnC = -mn * C;
;   for (int r = 0; r < 16; ++r) p0[r] = fmaf(p0[r], C, mnC); for (int r = 0; r < 16; ++r) p1[r] = fmaf(p1[r], C, mnC);
; __device__ __forceinline__ void attn_body256(const bf16_t* __restrict__ Qb, const bf16_t* __restrict__ Kh, const bf16_t* __restrict__ Vh,
;                                              bf16_t* Ob, int seq, unsigned char* lds, float lam, int MODE, bf16_t* Ab, const float* wsub) {
;     ...
;     if (__any(alpha < 1.f)) { if (hi == 0) al_l[r32] = alpha; asm volatile("s_waitcnt lgkmcnt(0)" ::: "memory");
; #pragma unroll
;       for (int r = 0; r < 16; ++r) { const float a = al_l[crow(r, hi)];
; #pragma unroll
;         for (int d = 0; d < 8; ++d) o[d][r] *= a; } }
.Lat_x_rare:
	v_mov_b32_e32 v196, v194
	v_mov_b32_e32 v197, v195
	s_nop 1
	v_permlane32_swap_b32_e32 v194, v196
	v_permlane32_swap_b32_e32 v195, v197
	v_max_f32_e32 v194, v194, v196
	v_max_f32_e32 v195, v195, v197
	v_mov_b32_e32 v196, v194
	v_mov_b32_e32 v197, v195
	s_nop 1
	v_permlane16_swap_b32_e32 v194, v196
	v_permlane16_swap_b32_e32 v195, v197
	v_max_f32_e32 v194, v194, v196
	v_max_f32_e32 v195, v195, v197
	s_cmp_eq_u32 s13, 2
	s_cselect_b32 s8, 0xff7fffff, 0
	v_max_f32_e32 v200, s8, v194
	v_max_f32_e32 v201, s8, v195
	v_max_f32_e32 v196, 0, v200
	v_max_f32_e32 v198, 0, v201
	v_exp_f32_e64 v196, -v196
	v_exp_f32_e64 v198, -v198
	v_sub_f32_e32 v236, v236, v200
	v_sub_f32_e32 v237, v237, v200
	v_sub_f32_e32 v238, v238, v200
	v_sub_f32_e32 v239, v239, v200
	v_sub_f32_e32 v240, v240, v201
	v_sub_f32_e32 v241, v241, v201
	v_sub_f32_e32 v242, v242, v201
	v_sub_f32_e32 v243, v243, v201
	v_sub_f32_e32 v130, v130, v200
	v_sub_f32_e32 v131, v131, v200
	v_sub_f32_e32 v132, v132, v200
	v_sub_f32_e32 v133, v133, v200
	v_sub_f32_e32 v134, v134, v201
	v_sub_f32_e32 v135, v135, v201
	v_sub_f32_e32 v136, v136, v201
	v_sub_f32_e32 v137, v137, v201
	v_sub_f32_e32 v138, v138, v200
	v_sub_f32_e32 v139, v139, v200
	v_sub_f32_e32 v140, v140, v200
	v_sub_f32_e32 v141, v141, v200
	v_sub_f32_e32 v142, v142, v201
	v_sub_f32_e32 v143, v143, v201
	v_sub_f32_e32 v144, v144, v201
	v_sub_f32_e32 v145, v145, v201
	v_sub_f32_e32 v146, v146, v200
	v_sub_f32_e32 v147, v147, v200
	v_sub_f32_e32 v148, v148, v200
	v_sub_f32_e32 v149, v149, v200
	v_sub_f32_e32 v150, v150, v201
	v_sub_f32_e32 v151, v151, v201
	v_sub_f32_e32 v152, v152, v201
	v_sub_f32_e32 v153, v153, v201
	v_sub_f32_e32 v154, v154, v200
	v_sub_f32_e32 v155, v155, v200
	v_sub_f32_e32 v156, v156, v200
	v_sub_f32_e32 v157, v157, v200
	v_sub_f32_e32 v158, v158, v201
	v_sub_f32_e32 v159, v159, v201
	v_sub_f32_e32 v160, v160, v201
	v_sub_f32_e32 v161, v161, v201
	v_mul_f32_e32 v250, v250, v196
	v_mul_f32_e32 v234, v234, v198
	v_pk_mul_f32 v[2:3], v[2:3], v[196:197] op_sel_hi:[1,0]
	v_pk_mul_f32 v[4:5], v[4:5], v[196:197] op_sel_hi:[1,0]
	v_pk_mul_f32 v[6:7], v[6:7], v[198:199] op_sel_hi:[1,0]
	v_pk_mul_f32 v[8:9], v[8:9], v[198:199] op_sel_hi:[1,0]
	v_pk_mul_f32 v[10:11], v[10:11], v[196:197] op_sel_hi:[1,0]
	v_pk_mul_f32 v[12:13], v[12:13], v[196:197] op_sel_hi:[1,0]
	v_pk_mul_f32 v[14:15], v[14:15], v[198:199] op_sel_hi:[1,0]
	v_pk_mul_f32 v[16:17], v[16:17], v[198:199] op_sel_hi:[1,0]
	v_pk_mul_f32 v[114:115], v[114:115], v[196:197] op_sel_hi:[1,0]
	v_pk_mul_f32 v[116:117], v[116:117], v[196:197] op_sel_hi:[1,0]
	v_pk_mul_f32 v[118:119], v[118:119], v[198:199] op_sel_hi:[1,0]
	v_pk_mul_f32 v[120:121], v[120:121], v[198:199] op_sel_hi:[1,0]
	v_pk_mul_f32 v[122:123], v[122:123], v[196:197] op_sel_hi:[1,0]
	v_pk_mul_f32 v[124:125], v[124:125], v[196:197] op_sel_hi:[1,0]
	v_pk_mul_f32 v[126:127], v[126:127], v[198:199] op_sel_hi:[1,0]
	v_pk_mul_f32 v[128:129], v[128:129], v[198:199] op_sel_hi:[1,0]
	v_pk_mul_f32 v[98:99], v[98:99], v[196:197] op_sel_hi:[1,0]
	v_pk_mul_f32 v[100:101], v[100:101], v[196:197] op_sel_hi:[1,0]
	v_pk_mul_f32 v[102:103], v[102:103], v[198:199] op_sel_hi:[1,0]
	v_pk_mul_f32 v[104:105], v[104:105], v[198:199] op_sel_hi:[1,0]
	v_pk_mul_f32 v[106:107], v[106:107], v[196:197] op_sel_hi:[1,0]
	v_pk_mul_f32 v[108:109], v[108:109], v[196:197] op_sel_hi:[1,0]
	v_pk_mul_f32 v[110:111], v[110:111], v[198:199] op_sel_hi:[1,0]
	v_pk_mul_f32 v[112:113], v[112:113], v[198:199] op_sel_hi:[1,0]
	v_pk_mul_f32 v[82:83], v[82:83], v[196:197] op_sel_hi:[1,0]
	v_pk_mul_f32 v[84:85], v[84:85], v[196:197] op_sel_hi:[1,0]
	v_pk_mul_f32 v[86:87], v[86:87], v[198:199] op_sel_hi:[1,0]
	v_pk_mul_f32 v[88:89], v[88:89], v[198:199] op_sel_hi:[1,0]
	v_pk_mul_f32 v[90:91], v[90:91], v[196:197] op_sel_hi:[1,0]
	v_pk_mul_f32 v[92:93], v[92:93], v[196:197] op_sel_hi:[1,0]
	v_pk_mul_f32 v[94:95], v[94:95], v[198:199] op_sel_hi:[1,0]
	v_pk_mul_f32 v[96:97], v[96:97], v[198:199] op_sel_hi:[1,0]
	v_pk_mul_f32 v[66:67], v[66:67], v[196:197] op_sel_hi:[1,0]
	v_pk_mul_f32 v[68:69], v[68:69], v[196:197] op_sel_hi:[1,0]
	v_pk_mul_f32 v[70:71], v[70:71], v[198:199] op_sel_hi:[1,0]
	v_pk_mul_f32 v[72:73], v[72:73], v[198:199] op_sel_hi:[1,0]
	v_pk_mul_f32 v[74:75], v[74:75], v[196:197] op_sel_hi:[1,0]
	v_pk_mul_f32 v[76:77], v[76:77], v[196:197] op_sel_hi:[1,0]
	v_pk_mul_f32 v[78:79], v[78:79], v[198:199] op_sel_hi:[1,0]
	v_pk_mul_f32 v[80:81], v[80:81], v[198:199] op_sel_hi:[1,0]
	v_pk_mul_f32 v[50:51], v[50:51], v[196:197] op_sel_hi:[1,0]
	v_pk_mul_f32 v[52:53], v[52:53], v[196:197] op_sel_hi:[1,0]
	v_pk_mul_f32 v[54:55], v[54:55], v[198:199] op_sel_hi:[1,0]
	v_pk_mul_f32 v[56:57], v[56:57], v[198:199] op_sel_hi:[1,0]
	v_pk_mul_f32 v[58:59], v[58:59], v[196:197] op_sel_hi:[1,0]
	v_pk_mul_f32 v[60:61], v[60:61], v[196:197] op_sel_hi:[1,0]
	v_pk_mul_f32 v[62:63], v[62:63], v[198:199] op_sel_hi:[1,0]
	v_pk_mul_f32 v[64:65], v[64:65], v[198:199] op_sel_hi:[1,0]
	v_pk_mul_f32 v[34:35], v[34:35], v[196:197] op_sel_hi:[1,0]
	v_pk_mul_f32 v[36:37], v[36:37], v[196:197] op_sel_hi:[1,0]
	v_pk_mul_f32 v[38:39], v[38:39], v[198:199] op_sel_hi:[1,0]
	v_pk_mul_f32 v[40:41], v[40:41], v[198:199] op_sel_hi:[1,0]
	v_pk_mul_f32 v[42:43], v[42:43], v[196:197] op_sel_hi:[1,0]
	v_pk_mul_f32 v[44:45], v[44:45], v[196:197] op_sel_hi:[1,0]
	v_pk_mul_f32 v[46:47], v[46:47], v[198:199] op_sel_hi:[1,0]
	v_pk_mul_f32 v[48:49], v[48:49], v[198:199] op_sel_hi:[1,0]
	v_pk_mul_f32 v[18:19], v[18:19], v[196:197] op_sel_hi:[1,0]
	v_pk_mul_f32 v[20:21], v[20:21], v[196:197] op_sel_hi:[1,0]
	v_pk_mul_f32 v[22:23], v[22:23], v[198:199] op_sel_hi:[1,0]
	v_pk_mul_f32 v[24:25], v[24:25], v[198:199] op_sel_hi:[1,0]
	v_pk_mul_f32 v[26:27], v[26:27], v[196:197] op_sel_hi:[1,0]
	v_pk_mul_f32 v[28:29], v[28:29], v[196:197] op_sel_hi:[1,0]
	v_pk_mul_f32 v[30:31], v[30:31], v[198:199] op_sel_hi:[1,0]
	v_pk_mul_f32 v[32:33], v[32:33], v[198:199] op_sel_hi:[1,0]

; __device__ __forceinline__ void partialSM(f32x16& p0, f32x16& p1, float& m_reg, float& mn, float& alpha) {
;   constexpr float C = SCALE * 1.4426950408889634f;
;   float pmax = p0[0]; for (int r = 1; r < 16; ++r) pmax = fmaxf(pmax, p0[r]); for (int r = 0; r < 16; ++r) pmax = fmaxf(pmax, p1[r]);
;   { auto rr = __builtin_amdgcn_permlane32_swap(__float_as_uint(pmax), __float_as_uint(pmax), false, false);
;     pmax = fmaxf(__uint_as_float(rr[0]), __uint_as_float(rr[1])); }
;   if (__builtin_expect(__all(pmax - m_reg <= THR / SCALE), 1)) { mn = m_reg; alpha = 1.f; }
;   else { mn = fmaxf(m_reg, pmax); alpha = __builtin_amdgcn_exp2f((m_reg - mn) * C); m_reg = mn; }
;   float mnC = -mn * C;
;   for (int r = 0; r < 16; ++r) p0[r] = fmaf(p0[r], C, mnC); for (int r = 0; r < 16; ++r) p1[r] = fmaf(p1[r], C, mnC);
;   for (int r = 0; r < 16; ++r) p0[r] = __builtin_amdgcn_exp2f(p0[r]);
; }
; __device__ __forceinline__ void finishSM(f32x16& p0, f32x16& p1, float alpha, float& l_reg, bf16x8& pa0, bf16x8& pa1, bf16x8& pa2, bf16x8& pa3) {
;   for (int r = 0; r < 16; ++r) p1[r] = __builtin_amdgcn_exp2f(p1[r]);
;   float ps = 0; for (int r = 0; r < 16; ++r) ps += p0[r]; for (int r = 0; r < 16; ++r) ps += p1[r];
;   { auto rr = __builtin_amdgcn_permlane32_swap(__float_as_uint(ps), __float_as_uint(ps), false, false);
;     ps = __uint_as_float(rr[0]) + __uint_as_float(rr[1]); }
;   l_reg = l_reg * alpha + ps;
;     ...
;   PK4(p0, 0, pa0); PK4(p0, 8, pa1); PK4(p1, 0, pa2); PK4(p1, 8, pa3);
;     ...
; }
; __device__ __forceinline__ void qkt(f32x16& p0, f32x16& p1, const bf16_t* Ks, const bf16x8* qr, int r32, int hi) {
;   p0 = f32x16{}; p1 = f32x16{};
;   for (int d0 = 0; d0 < 8; ++d0) { int cb = (d0 * 16 + hi * 8) * 2;
;     bf16x8 b0 = *reinterpret_cast<const bf16x8*>((const char*)Ks + KSWZ(r32, cb));
;     bf16x8 b1 = *reinterpret_cast<const bf16x8*>((const char*)Ks + KSWZ(32 + r32, cb));
;     p0 = __builtin_amdgcn_mfma_f32_32x32x16_bf16(b0, qr[d0], p0, 0, 0, 0);
;     p1 = __builtin_amdgcn_mfma_f32_32x32x16_bf16(b1, qr[d0], p1, 0, 0, 0); }
; }
.Lat_y_nodma:
.Lat_y_qk:
	s_add_i32 s8, s13, -2
	s_and_b32 s25, s8, 1
	s_lshl_b32 s24, s25, 14
	s_add_i32 s8, s24, 0x10000
	v_add_u32_e32 v230, s8, v232
	v_add_u32_e32 v247, s8, v233
	v_add_u32_e32 v228, s8, v246
	v_add_u32_e32 v245, s8, v249
	s_setprio 1
	ds_read_b128 v[194:197], v230
	ds_read_b128 v[198:201], v230 offset:4096
	ds_read_b128 v[202:205], v230 offset:8192
	ds_read_b128 v[206:209], v230 offset:12288
	ds_read_b128 v[210:213], v247
	ds_read_b128 v[214:217], v247 offset:4096
	s_waitcnt lgkmcnt(5)
	v_mfma_f32_16x16x32_bf16 v[130:133], v[194:197], v[162:165], v[236:239]
	v_mfma_f32_16x16x32_bf16 v[134:137], v[194:197], v[178:181], v[240:243]
	ds_read_b128 v[194:197], v247 offset:8192
	s_waitcnt lgkmcnt(5)
	v_mfma_f32_16x16x32_bf16 v[138:141], v[198:201], v[162:165], v[236:239]
	v_mfma_f32_16x16x32_bf16 v[142:145], v[198:201], v[178:181], v[240:243]
	ds_read_b128 v[198:201], v247 offset:12288
	s_waitcnt lgkmcnt(5)
	v_mfma_f32_16x16x32_bf16 v[146:149], v[202:205], v[162:165], v[236:239]
	v_mfma_f32_16x16x32_bf16 v[150:153], v[202:205], v[178:181], v[240:243]
	ds_read_b128 v[202:205], v228
	s_waitcnt lgkmcnt(5)
	v_mfma_f32_16x16x32_bf16 v[154:157], v[206:209], v[162:165], v[236:239]
	v_mfma_f32_16x16x32_bf16 v[158:161], v[206:209], v[178:181], v[240:243]
	ds_read_b128 v[206:209], v228 offset:4096
	s_waitcnt lgkmcnt(5)
	v_mfma_f32_16x16x32_bf16 v[130:133], v[210:213], v[166:169], v[130:133]
	v_mfma_f32_16x16x32_bf16 v[134:137], v[210:213], v[182:185], v[134:137]
	ds_read_b128 v[210:213], v228 offset:8192
	s_waitcnt lgkmcnt(5)
	v_mfma_f32_16x16x32_bf16 v[138:141], v[214:217], v[166:169], v[138:141]
	v_mfma_f32_16x16x32_bf16 v[142:145], v[214:217], v[182:185], v[142:145]
	ds_read_b128 v[214:217], v228 offset:12288
	s_waitcnt lgkmcnt(5)
	v_mfma_f32_16x16x32_bf16 v[146:149], v[194:197], v[166:169], v[146:149]
	v_mfma_f32_16x16x32_bf16 v[150:153], v[194:197], v[182:185], v[150:153]
	ds_read_b128 v[194:197], v245
	s_waitcnt lgkmcnt(5)
	v_mfma_f32_16x16x32_bf16 v[154:157], v[198:201], v[166:169], v[154:157]
	v_mfma_f32_16x16x32_bf16 v[158:161], v[198:201], v[182:185], v[158:161]
	ds_read_b128 v[198:201], v245 offset:4096
	s_waitcnt lgkmcnt(5)
	v_mfma_f32_16x16x32_bf16 v[130:133], v[202:205], v[170:173], v[130:133]
	v_mfma_f32_16x16x32_bf16 v[134:137], v[202:205], v[186:189], v[134:137]
	ds_read_b128 v[202:205], v245 offset:8192
	s_waitcnt lgkmcnt(5)
	v_mfma_f32_16x16x32_bf16 v[138:141], v[206:209], v[170:173], v[138:141]
	v_mfma_f32_16x16x32_bf16 v[142:145], v[206:209], v[186:189], v[142:145]
	ds_read_b128 v[206:209], v245 offset:12288
	s_waitcnt lgkmcnt(5)
	v_mfma_f32_16x16x32_bf16 v[146:149], v[210:213], v[170:173], v[146:149]
	v_mfma_f32_16x16x32_bf16 v[150:153], v[210:213], v[186:189], v[150:153]
	s_waitcnt lgkmcnt(4)
	v_mfma_f32_16x16x32_bf16 v[154:157], v[214:217], v[170:173], v[154:157]
	v_mfma_f32_16x16x32_bf16 v[158:161], v[214:217], v[186:189], v[158:161]
	s_waitcnt lgkmcnt(3)
	v_mfma_f32_16x16x32_bf16 v[130:133], v[194:197], v[174:177], v[130:133]
	v_mfma_f32_16x16x32_bf16 v[134:137], v[194:197], v[190:193], v[134:137]
	s_waitcnt lgkmcnt(2)
	v_mfma_f32_16x16x32_bf16 v[138:141], v[198:201], v[174:177], v[138:141]
	v_mfma_f32_16x16x32_bf16 v[142:145], v[198:201], v[190:193], v[142:145]
	s_waitcnt lgkmcnt(1)
	v_mfma_f32_16x16x32_bf16 v[146:149], v[202:205], v[174:177], v[146:149]
	v_mfma_f32_16x16x32_bf16 v[150:153], v[202:205], v[190:193], v[150:153]
	s_waitcnt lgkmcnt(0)
	v_mfma_f32_16x16x32_bf16 v[154:157], v[206:209], v[174:177], v[154:157]
	v_mfma_f32_16x16x32_bf16 v[158:161], v[206:209], v[190:193], v[158:161]
	s_setprio 0
	s_nop 6
	v_max3_f32 v194, v130, v131, v132
	v_max3_f32 v194, v194, v133, v138
	v_max3_f32 v194, v194, v139, v140
	v_max3_f32 v194, v194, v141, v146
	v_max3_f32 v194, v194, v147, v148
	v_max3_f32 v194, v194, v149, v154
	v_max3_f32 v194, v194, v155, v156
	v_max_f32_e32 v194, v194, v157
	v_max3_f32 v195, v134, v135, v136
	v_max3_f32 v195, v195, v137, v142
	v_max3_f32 v195, v195, v143, v144
	v_max3_f32 v195, v195, v145, v150
	v_max3_f32 v195, v195, v151, v152
	v_max3_f32 v195, v195, v153, v158
	v_max3_f32 v195, v195, v159, v160
	v_max_f32_e32 v195, v195, v161
	v_max_f32_e32 v196, v194, v195
	v_cmp_nge_f32_e32 vcc, 0x4138aa3b, v196
	s_cbranch_vccnz .Lat_y_rare
	s_cmp_lg_u32 s13, 2
	s_cbranch_scc1 .Lat_y_noresc
